# A/B: v3, K-loop flips deleted, static s_setprio 1 for waves 4-7 from kernel entry
# baseline (speedup 1.0000x reference)
_Z3fwd4Args:
	s_mov_b64 s[16:17], s[0:1]
	v_mov_b32_e32 v1, v0
	s_load_dword s73, s[0:1], 0x98
	s_mov_b64 s[14:15], s[0:1]
	s_mov_b32 s18, s2
	s_mov_b32 s72, s2
	v_readfirstlane_b32 s33, v1
	s_nop 3
	s_cmp_lt_u32 s33, 0x100
	s_cbranch_scc1 .Lprio_old
	s_setprio 1
.Lprio_old:
	s_waitcnt lgkmcnt(0)
	s_mov_b32 s0, s73
	s_load_dwordx2 s[10:11], s[16:17], 0x90
	s_movk_i32 s0, 0xc00
	v_cmp_gt_i32_e32 vcc, s0, v1
	s_and_saveexec_b64 s[0:1], vcc
	s_cbranch_execz .LBB0_3
	v_lshl_add_u32 v3, v1, 2, 0
	v_add_u32_e32 v2, 0xfffffe00, v1
	v_add_u32_e32 v3, 0x21000, v3
	s_mov_b64 s[2:3], 0
	v_mov_b32_e32 v4, 0
	s_movk_i32 s4, 0x9ff
